# stack9 + instruction selection: GEMM accumulator clears as 64-bit moves (63 fewer VALU per unit per wave)
# speedup vs baseline: 1.0052x; 1.0052x over previous
.LBB8_265:
	s_ashr_i32 s17, s16, 31
	s_lshl_b64 s[60:61], s[16:17], 21
	s_add_u32 s60, s54, s60
	s_addc_u32 s61, s55, s61
	s_and_b64 s[64:65], s[0:1], exec
	s_cselect_b32 s17, s61, s71
	s_cselect_b32 s85, s60, s70
	s_ashr_i32 s15, s14, 31
	s_lshl_b64 s[64:65], s[14:15], 21
	s_add_u32 s64, s4, s64
	s_addc_u32 s65, s5, s65
	s_and_b64 s[72:73], s[0:1], exec
	s_cselect_b32 s15, s65, s29
	s_cselect_b32 s86, s64, s28
	s_add_u32 s70, s70, 0x100080
	s_addc_u32 s71, s71, 0
	s_add_u32 s87, s28, 0x100
	v_mov_b32_e32 v0, 0
	s_addc_u32 s92, s29, 0
	s_mov_b32 s93, -2
	v_mov_b32_e32 v1, v0
	v_mov_b64_e32 v[2:3], 0
	v_mov_b64_e32 v[4:5], 0
	v_mov_b64_e32 v[6:7], 0
	v_mov_b64_e32 v[8:9], 0
	v_mov_b64_e32 v[10:11], 0
	v_mov_b64_e32 v[16:17], 0
	v_mov_b64_e32 v[18:19], 0
	v_mov_b64_e32 v[24:25], 0
	v_mov_b64_e32 v[26:27], 0
	v_mov_b64_e32 v[32:33], 0
	v_mov_b64_e32 v[34:35], 0
	v_mov_b64_e32 v[40:41], 0
	v_mov_b64_e32 v[42:43], 0
	v_mov_b64_e32 v[48:49], 0
	v_mov_b64_e32 v[50:51], 0
	v_mov_b64_e32 v[12:13], 0
	v_mov_b64_e32 v[14:15], 0
	v_mov_b64_e32 v[20:21], 0
	v_mov_b64_e32 v[22:23], 0
	v_mov_b64_e32 v[28:29], 0
	v_mov_b64_e32 v[30:31], 0
	v_mov_b64_e32 v[36:37], 0
	v_mov_b64_e32 v[38:39], 0
	v_mov_b64_e32 v[44:45], 0
	v_mov_b64_e32 v[46:47], 0
	v_mov_b64_e32 v[52:53], 0
	v_mov_b64_e32 v[54:55], 0
	v_mov_b64_e32 v[56:57], 0
	v_mov_b64_e32 v[58:59], 0
	v_mov_b64_e32 v[60:61], 0
	v_mov_b64_e32 v[62:63], 0
	v_mov_b64_e32 v[64:65], 0
	v_mov_b64_e32 v[66:67], 0
	v_mov_b64_e32 v[68:69], 0
	v_mov_b64_e32 v[70:71], 0
	v_mov_b64_e32 v[72:73], 0
	v_mov_b64_e32 v[74:75], 0
	v_mov_b64_e32 v[80:81], 0
	v_mov_b64_e32 v[82:83], 0
	v_mov_b64_e32 v[88:89], 0
	v_mov_b64_e32 v[90:91], 0
	v_mov_b64_e32 v[96:97], 0
	v_mov_b64_e32 v[98:99], 0
	v_mov_b64_e32 v[104:105], 0
	v_mov_b64_e32 v[106:107], 0
	v_mov_b64_e32 v[112:113], 0
	v_mov_b64_e32 v[114:115], 0
	v_mov_b64_e32 v[76:77], 0
	v_mov_b64_e32 v[78:79], 0
	v_mov_b64_e32 v[84:85], 0
	v_mov_b64_e32 v[86:87], 0
	v_mov_b64_e32 v[92:93], 0
	v_mov_b64_e32 v[94:95], 0
	v_mov_b64_e32 v[100:101], 0
	v_mov_b64_e32 v[102:103], 0
	v_mov_b64_e32 v[108:109], 0
	v_mov_b64_e32 v[110:111], 0
	v_mov_b64_e32 v[116:117], 0
	v_mov_b64_e32 v[118:119], 0
	v_mov_b64_e32 v[120:121], 0
	v_mov_b64_e32 v[122:123], 0
	v_mov_b64_e32 v[124:125], 0
	v_mov_b64_e32 v[126:127], 0

.LBB8_843:
	s_ashr_i32 s17, s16, 31
	s_lshl_b64 s[18:19], s[16:17], 20
	s_add_u32 s18, s70, s18
	s_addc_u32 s19, s71, s19
	s_and_b64 s[20:21], s[0:1], exec
	s_cselect_b32 s5, s19, s25
	s_cselect_b32 s17, s18, s24
	s_ashr_i32 s15, s14, 31
	s_lshl_b64 s[20:21], s[14:15], 20
	s_add_u32 s20, s90, s20
	s_addc_u32 s21, s91, s21
	s_and_b64 s[34:35], s[0:1], exec
	s_cselect_b32 s15, s21, s29
	s_cselect_b32 s23, s20, s28
	s_add_u32 s24, s24, 0x80080
	s_addc_u32 s25, s25, 0
	s_add_u32 s56, s28, 0x100
	v_mov_b32_e32 v0, 0
	s_addc_u32 s57, s29, 0
	s_mov_b32 s58, -2
	v_mov_b32_e32 v1, v0
	v_mov_b64_e32 v[2:3], 0
	v_mov_b64_e32 v[4:5], 0
	v_mov_b64_e32 v[6:7], 0
	v_mov_b64_e32 v[16:17], 0
	v_mov_b64_e32 v[18:19], 0
	v_mov_b64_e32 v[20:21], 0
	v_mov_b64_e32 v[22:23], 0
	v_mov_b64_e32 v[32:33], 0
	v_mov_b64_e32 v[34:35], 0
	v_mov_b64_e32 v[36:37], 0
	v_mov_b64_e32 v[38:39], 0
	v_mov_b64_e32 v[52:53], 0
	v_mov_b64_e32 v[54:55], 0
	v_mov_b64_e32 v[56:57], 0
	v_mov_b64_e32 v[58:59], 0
	v_mov_b64_e32 v[8:9], 0
	v_mov_b64_e32 v[10:11], 0
	v_mov_b64_e32 v[12:13], 0
	v_mov_b64_e32 v[14:15], 0
	v_mov_b64_e32 v[24:25], 0
	v_mov_b64_e32 v[26:27], 0
	v_mov_b64_e32 v[28:29], 0
	v_mov_b64_e32 v[30:31], 0
	v_mov_b64_e32 v[40:41], 0
	v_mov_b64_e32 v[42:43], 0
	v_mov_b64_e32 v[44:45], 0
	v_mov_b64_e32 v[46:47], 0
	v_mov_b64_e32 v[64:65], 0
	v_mov_b64_e32 v[66:67], 0
	v_mov_b64_e32 v[68:69], 0
	v_mov_b64_e32 v[70:71], 0
	v_mov_b64_e32 v[76:77], 0
	v_mov_b64_e32 v[78:79], 0
	v_mov_b64_e32 v[84:85], 0
	v_mov_b64_e32 v[86:87], 0
	v_mov_b64_e32 v[104:105], 0
	v_mov_b64_e32 v[106:107], 0
	v_mov_b64_e32 v[108:109], 0
	v_mov_b64_e32 v[110:111], 0
	v_mov_b64_e32 v[128:129], 0
	v_mov_b64_e32 v[130:131], 0
	v_mov_b64_e32 v[132:133], 0
	v_mov_b64_e32 v[134:135], 0
	v_mov_b64_e32 v[148:149], 0
	v_mov_b64_e32 v[150:151], 0
	v_mov_b64_e32 v[152:153], 0
	v_mov_b64_e32 v[154:155], 0
	v_mov_b64_e32 v[92:93], 0
	v_mov_b64_e32 v[94:95], 0
	v_mov_b64_e32 v[96:97], 0
	v_mov_b64_e32 v[98:99], 0
	v_mov_b64_e32 v[116:117], 0
	v_mov_b64_e32 v[118:119], 0
	v_mov_b64_e32 v[120:121], 0
	v_mov_b64_e32 v[122:123], 0
	v_mov_b64_e32 v[136:137], 0
	v_mov_b64_e32 v[138:139], 0
	v_mov_b64_e32 v[140:141], 0
	v_mov_b64_e32 v[142:143], 0
	v_mov_b64_e32 v[160:161], 0
	v_mov_b64_e32 v[162:163], 0
	v_mov_b64_e32 v[164:165], 0
	v_mov_b64_e32 v[166:167], 0

.LBB8_960:
	s_ashr_i32 s19, s18, 31
	s_lshl_b64 s[20:21], s[18:19], 21
	s_add_u32 s20, s64, s20
	s_addc_u32 s21, s65, s21
	s_and_b64 s[22:23], s[4:5], exec
	s_cselect_b32 s19, s21, s41
	s_cselect_b32 s25, s20, s40
	s_ashr_i32 s17, s16, 31
	s_lshl_b64 s[22:23], s[16:17], 21
	v_readlane_b32 s42, v254, 43
	v_readlane_b32 s43, v254, 44
	s_add_u32 s22, s42, s22
	s_addc_u32 s23, s43, s23
	s_and_b64 s[42:43], s[4:5], exec
	s_cselect_b32 s17, s23, s29
	s_cselect_b32 s66, s22, s28
	s_add_u32 s40, s40, 0x100080
	s_addc_u32 s41, s41, 0
	s_add_u32 s67, s28, 0x100
	v_mov_b32_e32 v0, 0
	s_addc_u32 s68, s29, 0
	s_mov_b32 s69, -2
	s_waitcnt lgkmcnt(0)
	v_mov_b32_e32 v1, v0
	v_mov_b64_e32 v[2:3], 0
	v_mov_b64_e32 v[4:5], 0
	v_mov_b64_e32 v[6:7], 0
	v_mov_b64_e32 v[16:17], 0
	v_mov_b64_e32 v[18:19], 0
	v_mov_b64_e32 v[20:21], 0
	v_mov_b64_e32 v[22:23], 0
	v_mov_b64_e32 v[32:33], 0
	v_mov_b64_e32 v[34:35], 0
	v_mov_b64_e32 v[36:37], 0
	v_mov_b64_e32 v[38:39], 0
	v_mov_b64_e32 v[48:49], 0
	v_mov_b64_e32 v[50:51], 0
	v_mov_b64_e32 v[52:53], 0
	v_mov_b64_e32 v[54:55], 0
	v_mov_b64_e32 v[8:9], 0
	v_mov_b64_e32 v[10:11], 0
	v_mov_b64_e32 v[12:13], 0
	v_mov_b64_e32 v[14:15], 0
	v_mov_b64_e32 v[24:25], 0
	v_mov_b64_e32 v[26:27], 0
	v_mov_b64_e32 v[28:29], 0
	v_mov_b64_e32 v[30:31], 0
	v_mov_b64_e32 v[40:41], 0
	v_mov_b64_e32 v[42:43], 0
	v_mov_b64_e32 v[44:45], 0
	v_mov_b64_e32 v[46:47], 0
	v_mov_b64_e32 v[56:57], 0
	v_mov_b64_e32 v[58:59], 0
	v_mov_b64_e32 v[60:61], 0
	v_mov_b64_e32 v[62:63], 0
	v_mov_b64_e32 v[64:65], 0
	v_mov_b64_e32 v[66:67], 0
	v_mov_b64_e32 v[68:69], 0
	v_mov_b64_e32 v[70:71], 0
	v_mov_b64_e32 v[92:93], 0
	v_mov_b64_e32 v[94:95], 0
	v_mov_b64_e32 v[100:101], 0
	v_mov_b64_e32 v[102:103], 0
	v_mov_b64_e32 v[112:113], 0
	v_mov_b64_e32 v[114:115], 0
	v_mov_b64_e32 v[116:117], 0
	v_mov_b64_e32 v[118:119], 0
	v_mov_b64_e32 v[128:129], 0
	v_mov_b64_e32 v[130:131], 0
	v_mov_b64_e32 v[132:133], 0
	v_mov_b64_e32 v[134:135], 0
	v_mov_b64_e32 v[72:73], 0
	v_mov_b64_e32 v[74:75], 0
	v_mov_b64_e32 v[80:81], 0
	v_mov_b64_e32 v[82:83], 0
	v_mov_b64_e32 v[104:105], 0
	v_mov_b64_e32 v[106:107], 0
	v_mov_b64_e32 v[108:109], 0
	v_mov_b64_e32 v[110:111], 0
	v_mov_b64_e32 v[120:121], 0
	v_mov_b64_e32 v[122:123], 0
	v_mov_b64_e32 v[124:125], 0
	v_mov_b64_e32 v[126:127], 0
	v_mov_b64_e32 v[136:137], 0
	v_mov_b64_e32 v[138:139], 0
	v_mov_b64_e32 v[140:141], 0
	v_mov_b64_e32 v[142:143], 0

.LBB8_1051:
	s_ashr_i32 s25, s24, 31
	s_lshl_b64 s[34:35], s[24:25], 21
	s_add_u32 s34, s54, s34
	s_addc_u32 s35, s55, s35
	s_and_b64 s[40:41], s[0:1], exec
	s_cselect_b32 s25, s35, s45
	s_cselect_b32 s63, s34, s44
	s_ashr_i32 s23, s22, 31
	s_lshl_b64 s[40:41], s[22:23], 21
	s_add_u32 s40, s92, s40
	s_addc_u32 s41, s93, s41
	s_and_b64 s[64:65], s[0:1], exec
	s_cselect_b32 s23, s41, s29
	s_cselect_b32 s64, s40, s28
	v_lshl_or_b32 v160, s43, 8, v168
	s_ashr_i32 s43, s42, 31
	s_lshr_b32 s43, s43, 29
	v_lshl_add_u32 v158, s42, 8, v166
	s_add_i32 s42, s42, s43
	s_ashr_i32 s42, s42, 3
	s_ashr_i32 s43, s42, 31
	s_lshl_b64 s[42:43], s[42:43], 16
	s_add_u32 s42, s26, s42
	v_ashrrev_i32_e32 v161, 31, v160
	s_addc_u32 s43, s27, s43
	v_lshl_add_u64 v[162:163], v[160:161], 2, s[42:43]
	s_add_u32 s42, s44, 0x100080
	s_addc_u32 s43, s45, 0
	v_ashrrev_i32_e32 v159, 31, v158
	s_add_u32 s65, s28, 0x100
	v_mov_b32_e32 v16, 0
	v_lshl_add_u64 v[164:165], v[158:159], 2, s[6:7]
	s_addc_u32 s66, s29, 0
	s_mov_b32 s67, -2
	v_mov_b32_e32 v17, v16
	v_mov_b64_e32 v[18:19], 0
	v_mov_b64_e32 v[20:21], 0
	v_mov_b64_e32 v[22:23], 0
	v_mov_b64_e32 v[32:33], 0
	v_mov_b64_e32 v[34:35], 0
	v_mov_b64_e32 v[36:37], 0
	v_mov_b64_e32 v[38:39], 0
	v_mov_b64_e32 v[48:49], 0
	v_mov_b64_e32 v[50:51], 0
	v_mov_b64_e32 v[52:53], 0
	v_mov_b64_e32 v[54:55], 0
	v_mov_b64_e32 v[64:65], 0
	v_mov_b64_e32 v[66:67], 0
	v_mov_b64_e32 v[68:69], 0
	v_mov_b64_e32 v[70:71], 0
	v_mov_b64_e32 v[24:25], 0
	v_mov_b64_e32 v[26:27], 0
	v_mov_b64_e32 v[28:29], 0
	v_mov_b64_e32 v[30:31], 0
	v_mov_b64_e32 v[40:41], 0
	v_mov_b64_e32 v[42:43], 0
	v_mov_b64_e32 v[44:45], 0
	v_mov_b64_e32 v[46:47], 0
	v_mov_b64_e32 v[56:57], 0
	v_mov_b64_e32 v[58:59], 0
	v_mov_b64_e32 v[60:61], 0
	v_mov_b64_e32 v[62:63], 0
	v_mov_b64_e32 v[72:73], 0
	v_mov_b64_e32 v[74:75], 0
	v_mov_b64_e32 v[76:77], 0
	v_mov_b64_e32 v[78:79], 0
	v_mov_b64_e32 v[80:81], 0
	v_mov_b64_e32 v[82:83], 0
	v_mov_b64_e32 v[84:85], 0
	v_mov_b64_e32 v[86:87], 0
	v_mov_b64_e32 v[96:97], 0
	v_mov_b64_e32 v[98:99], 0
	v_mov_b64_e32 v[100:101], 0
	v_mov_b64_e32 v[102:103], 0
	v_mov_b64_e32 v[112:113], 0
	v_mov_b64_e32 v[114:115], 0
	v_mov_b64_e32 v[116:117], 0
	v_mov_b64_e32 v[118:119], 0
	v_mov_b64_e32 v[128:129], 0
	v_mov_b64_e32 v[130:131], 0
	v_mov_b64_e32 v[132:133], 0
	v_mov_b64_e32 v[134:135], 0
	v_mov_b64_e32 v[88:89], 0
	v_mov_b64_e32 v[90:91], 0
	v_mov_b64_e32 v[92:93], 0
	v_mov_b64_e32 v[94:95], 0
	v_mov_b64_e32 v[104:105], 0
	v_mov_b64_e32 v[106:107], 0
	v_mov_b64_e32 v[108:109], 0
	v_mov_b64_e32 v[110:111], 0
	v_mov_b64_e32 v[120:121], 0
	v_mov_b64_e32 v[122:123], 0
	v_mov_b64_e32 v[124:125], 0
	v_mov_b64_e32 v[126:127], 0
	v_mov_b64_e32 v[136:137], 0
	v_mov_b64_e32 v[138:139], 0
	v_mov_b64_e32 v[140:141], 0
	v_mov_b64_e32 v[142:143], 0
	s_branch .LBB8_1053

.LBB8_1132:
	s_ashr_i32 s21, s20, 31
	s_lshl_b64 s[22:23], s[20:21], 23
	s_add_u32 s22, s36, s22
	s_addc_u32 s23, s37, s23
	s_and_b64 s[24:25], s[0:1], exec
	s_cselect_b32 s21, s23, s35
	s_cselect_b32 s53, s22, s34
	s_ashr_i32 s19, s18, 31
	s_lshl_b64 s[24:25], s[18:19], 23
	s_add_u32 s24, s88, s24
	s_addc_u32 s25, s89, s25
	s_and_b64 s[26:27], s[0:1], exec
	s_cselect_b32 s19, s25, s31
	s_cselect_b32 s54, s24, s30
	s_add_u32 s26, s34, 0x400080
	s_addc_u32 s27, s35, 0
	s_add_u32 s55, s30, 0x100
	v_mov_b32_e32 v0, 0
	s_addc_u32 s56, s31, 0
	s_mov_b32 s57, -2
	v_mov_b32_e32 v1, v0
	v_mov_b64_e32 v[2:3], 0
	v_mov_b64_e32 v[4:5], 0
	v_mov_b64_e32 v[6:7], 0
	v_mov_b64_e32 v[8:9], 0
	v_mov_b64_e32 v[10:11], 0
	v_mov_b64_e32 v[16:17], 0
	v_mov_b64_e32 v[18:19], 0
	v_mov_b64_e32 v[24:25], 0
	v_mov_b64_e32 v[26:27], 0
	v_mov_b64_e32 v[32:33], 0
	v_mov_b64_e32 v[34:35], 0
	v_mov_b64_e32 v[40:41], 0
	v_mov_b64_e32 v[42:43], 0
	v_mov_b64_e32 v[48:49], 0
	v_mov_b64_e32 v[50:51], 0
	v_mov_b64_e32 v[12:13], 0
	v_mov_b64_e32 v[14:15], 0
	v_mov_b64_e32 v[20:21], 0
	v_mov_b64_e32 v[22:23], 0
	v_mov_b64_e32 v[28:29], 0
	v_mov_b64_e32 v[30:31], 0
	v_mov_b64_e32 v[36:37], 0
	v_mov_b64_e32 v[38:39], 0
	v_mov_b64_e32 v[44:45], 0
	v_mov_b64_e32 v[46:47], 0
	v_mov_b64_e32 v[52:53], 0
	v_mov_b64_e32 v[54:55], 0
	v_mov_b64_e32 v[56:57], 0
	v_mov_b64_e32 v[58:59], 0
	v_mov_b64_e32 v[60:61], 0
	v_mov_b64_e32 v[62:63], 0
	v_mov_b64_e32 v[64:65], 0
	v_mov_b64_e32 v[66:67], 0
	v_mov_b64_e32 v[68:69], 0
	v_mov_b64_e32 v[70:71], 0
	v_mov_b64_e32 v[72:73], 0
	v_mov_b64_e32 v[74:75], 0
	v_mov_b64_e32 v[80:81], 0
	v_mov_b64_e32 v[82:83], 0
	v_mov_b64_e32 v[92:93], 0
	v_mov_b64_e32 v[94:95], 0
	v_mov_b64_e32 v[104:105], 0
	v_mov_b64_e32 v[106:107], 0
	v_mov_b64_e32 v[116:117], 0
	v_mov_b64_e32 v[118:119], 0
	v_mov_b64_e32 v[124:125], 0
	v_mov_b64_e32 v[126:127], 0
	v_mov_b64_e32 v[88:89], 0
	v_mov_b64_e32 v[90:91], 0
	v_mov_b64_e32 v[100:101], 0
	v_mov_b64_e32 v[102:103], 0
	v_mov_b64_e32 v[112:113], 0
	v_mov_b64_e32 v[114:115], 0
	v_mov_b64_e32 v[120:121], 0
	v_mov_b64_e32 v[122:123], 0
	v_mov_b64_e32 v[128:129], 0
	v_mov_b64_e32 v[130:131], 0
	v_mov_b64_e32 v[132:133], 0
	v_mov_b64_e32 v[134:135], 0
	v_mov_b64_e32 v[136:137], 0
	v_mov_b64_e32 v[138:139], 0
	v_mov_b64_e32 v[140:141], 0
	v_mov_b64_e32 v[142:143], 0
